# attention partial-output stores widened: 8 dwordx2 -> 4 dwordx4 per lane via v_permlane16_swap between lane rows (same bytes, same addresses)
# baseline (speedup 1.0000x reference)
; __device__ __forceinline__ void attention_item(LAS unsigned char* lds, const bf16* ZH, bf16* OP, float* LP, bf16* MIX, const float* qg, const float* kg, int item, int tid0) {
;     ...
;           const int i = 16 * w + lr, rb = 16 * jt0 + 4 * lg - 64 - i, lo_i = -(i + B.qi0), hi_i = B.m - 1 - i - B.qi0;
;           const float rbf = (float)rb, LO = (float)(lo_i > -64 ? lo_i : -64), HI = (float)(hi_i < 64 ? hi_i : 64);
;           const float L2E = 1.4426950408889634f, sdl = sd * L2E, sml = smax * L2E;
; #pragma unroll
;           for (int t = 0; t < 10; ++t)
; #pragma unroll
;             for (int rr = 0; rr < 4; ++rr) { const float relf = rbf + (float)(16 * t + rr);
;                 const float x = __builtin_fmaf(sT[t][rr], L2E, __builtin_fmaf(-sdl, __builtin_fabsf(relf), -sml));
;                 const bool ok = __builtin_amdgcn_fmed3f(relf, LO, HI) == relf;
;                 const float p = ok ? __builtin_amdgcn_exp2f(x) : 0.f; sT[t][rr] = p; lsum += p; } }
.LBB0_386:
	s_lshl_b32 s34, 1, s42
	v_cvt_f32_ubyte0_e32 v66, s34
	s_lshr_b32 s34, s47, s42
	s_add_i32 s34, s56, s34
	s_lshr_b32 s56, s47, s35
	s_lshl_b32 s57, s57, 7
	s_add_i32 s57, s57, s56
	v_lshlrev_b32_e32 v208, 2, v4
	v_mul_f32_e32 v213, v229, v66
	s_lshr_b32 s51, s64, s42
	v_add_u32_e32 v66, s57, v227
	v_or_b32_e32 v211, v5, v2
	v_add_u32_e32 v210, v210, v208
	v_lshlrev_b32_e32 v66, s35, v66
	v_sub_u32_e32 v210, v210, v211
	v_add_u32_e32 v212, s34, v211
	s_sub_i32 s35, s51, s34
	v_subrev_u32_e32 v210, 64, v210
	v_sub_u32_e32 v212, 0, v212
	v_xad_u32 v214, v211, -1, s35
	v_cvt_f32_i32_e32 v211, v210
	v_max_i32_e32 v210, 0xffffffc0, v212
	v_min_i32_e32 v212, 64, v214
	v_cvt_f32_i32_e32 v210, v210
	v_cvt_f32_i32_e32 v212, v212
	v_mul_f32_e32 v213, 0xbfb8aa3b, v213
	v_fma_f32 v214, v213, |v211|, v239
	v_fmac_f32_e32 v214, 0x3fb8aa3b, v186
	v_med3_f32 v186, v211, v210, v212
	v_cmp_eq_f32_e32 vcc, v186, v211
	v_exp_f32_e32 v186, v214
	v_add_f32_e32 v215, 1.0, v211
	v_fma_f32 v216, v213, |v215|, v239
	v_fmac_f32_e32 v216, 0x3fb8aa3b, v187
	v_med3_f32 v187, v215, v210, v212
	v_cndmask_b32_e32 v186, 0, v186, vcc
	v_cmp_eq_f32_e32 vcc, v187, v215
	v_exp_f32_e32 v187, v216
	v_add_f32_e32 v215, 2.0, v211
	v_fma_f32 v216, v213, |v215|, v239
	v_fmac_f32_e32 v216, 0x3fb8aa3b, v188
	v_med3_f32 v188, v215, v210, v212
	v_cndmask_b32_e32 v187, 0, v187, vcc
	v_cmp_eq_f32_e32 vcc, v188, v215
	v_exp_f32_e32 v188, v216
	v_add_f32_e32 v215, 0x40400000, v211
	v_fma_f32 v216, v213, |v215|, v239
	v_fmac_f32_e32 v216, 0x3fb8aa3b, v189
	v_med3_f32 v189, v215, v210, v212
	v_cndmask_b32_e32 v188, 0, v188, vcc
	v_cmp_eq_f32_e32 vcc, v189, v215
	v_exp_f32_e32 v189, v216
	v_add_f32_e32 v215, 0x41800000, v211
	v_fma_f32 v216, v213, |v215|, v239
	v_fmac_f32_e32 v216, 0x3fb8aa3b, v182
	v_med3_f32 v182, v215, v210, v212
	v_cndmask_b32_e32 v189, 0, v189, vcc
	v_cmp_eq_f32_e32 vcc, v182, v215
	v_exp_f32_e32 v182, v216
	v_add_f32_e32 v215, 0x41880000, v211
	v_fma_f32 v216, v213, |v215|, v239
	v_fmac_f32_e32 v216, 0x3fb8aa3b, v183
	v_med3_f32 v183, v215, v210, v212
	v_cndmask_b32_e32 v182, 0, v182, vcc
	v_cmp_eq_f32_e32 vcc, v183, v215
	v_exp_f32_e32 v183, v216
	v_add_f32_e32 v215, 0x41900000, v211
	v_fma_f32 v216, v213, |v215|, v239
	v_fmac_f32_e32 v216, 0x3fb8aa3b, v184
	v_med3_f32 v184, v215, v210, v212
	v_cndmask_b32_e32 v183, 0, v183, vcc
	v_cmp_eq_f32_e32 vcc, v184, v215
	v_exp_f32_e32 v184, v216
	v_add_f32_e32 v215, 0x41980000, v211
	v_fma_f32 v216, v213, |v215|, v239
	v_fmac_f32_e32 v216, 0x3fb8aa3b, v185
	v_med3_f32 v185, v215, v210, v212
	v_cndmask_b32_e32 v184, 0, v184, vcc
	v_cmp_eq_f32_e32 vcc, v185, v215
	v_exp_f32_e32 v185, v216
	v_add_f32_e32 v215, 0x42000000, v211
	v_fma_f32 v216, v213, |v215|, v239
	v_fmac_f32_e32 v216, 0x3fb8aa3b, v178
	v_med3_f32 v178, v215, v210, v212
	v_cndmask_b32_e32 v185, 0, v185, vcc
	v_cmp_eq_f32_e32 vcc, v178, v215
	v_exp_f32_e32 v178, v216
	v_add_f32_e32 v215, 0x42040000, v211
	v_fma_f32 v216, v213, |v215|, v239
	v_fmac_f32_e32 v216, 0x3fb8aa3b, v179
	v_med3_f32 v179, v215, v210, v212
	v_cndmask_b32_e32 v178, 0, v178, vcc
	v_cmp_eq_f32_e32 vcc, v179, v215
	v_exp_f32_e32 v179, v216
	v_add_f32_e32 v215, 0x42080000, v211
	v_fma_f32 v216, v213, |v215|, v239
	v_fmac_f32_e32 v216, 0x3fb8aa3b, v180
	v_med3_f32 v180, v215, v210, v212
	v_cndmask_b32_e32 v179, 0, v179, vcc
	v_cmp_eq_f32_e32 vcc, v180, v215
	v_exp_f32_e32 v180, v216
	v_add_f32_e32 v215, 0x420c0000, v211
	v_fma_f32 v216, v213, |v215|, v239
	v_fmac_f32_e32 v216, 0x3fb8aa3b, v181
	v_med3_f32 v181, v215, v210, v212
	v_cndmask_b32_e32 v180, 0, v180, vcc
	v_cmp_eq_f32_e32 vcc, v181, v215
	v_exp_f32_e32 v181, v216
	v_add_f32_e32 v215, 0x42400000, v211
	v_fma_f32 v216, v213, |v215|, v239
	v_fmac_f32_e32 v216, 0x3fb8aa3b, v174
	v_med3_f32 v174, v215, v210, v212
	v_cndmask_b32_e32 v181, 0, v181, vcc
	v_cmp_eq_f32_e32 vcc, v174, v215
	v_exp_f32_e32 v174, v216
	v_add_f32_e32 v215, 0x42440000, v211
	v_fma_f32 v216, v213, |v215|, v239
	v_fmac_f32_e32 v216, 0x3fb8aa3b, v175
	v_med3_f32 v175, v215, v210, v212
	v_cndmask_b32_e32 v174, 0, v174, vcc
	v_cmp_eq_f32_e32 vcc, v175, v215
	v_exp_f32_e32 v175, v216
	v_add_f32_e32 v215, 0x42480000, v211
	v_fma_f32 v216, v213, |v215|, v239
	v_fmac_f32_e32 v216, 0x3fb8aa3b, v176
	v_med3_f32 v176, v215, v210, v212
	v_cndmask_b32_e32 v175, 0, v175, vcc
	v_cmp_eq_f32_e32 vcc, v176, v215
	v_exp_f32_e32 v176, v216
	v_add_f32_e32 v215, 0x424c0000, v211
	v_fma_f32 v216, v213, |v215|, v239
	v_fmac_f32_e32 v216, 0x3fb8aa3b, v177
	v_med3_f32 v177, v215, v210, v212
	v_cndmask_b32_e32 v176, 0, v176, vcc
	v_cmp_eq_f32_e32 vcc, v177, v215
	v_exp_f32_e32 v177, v216
	v_add_f32_e32 v215, 0x42800000, v211
	v_fma_f32 v216, v213, |v215|, v239
	v_fmac_f32_e32 v216, 0x3fb8aa3b, v170
	v_med3_f32 v170, v215, v210, v212
	v_cndmask_b32_e32 v177, 0, v177, vcc
	v_cmp_eq_f32_e32 vcc, v170, v215
	v_exp_f32_e32 v170, v216
	v_add_f32_e32 v215, 0x42820000, v211
	v_fma_f32 v216, v213, |v215|, v239
	v_fmac_f32_e32 v216, 0x3fb8aa3b, v171
	v_med3_f32 v171, v215, v210, v212
	v_cndmask_b32_e32 v170, 0, v170, vcc
	v_cmp_eq_f32_e32 vcc, v171, v215
	v_exp_f32_e32 v171, v216
	v_add_f32_e32 v215, 0x42840000, v211
	v_fma_f32 v216, v213, |v215|, v239
	v_fmac_f32_e32 v216, 0x3fb8aa3b, v172
	v_med3_f32 v172, v215, v210, v212
	v_cndmask_b32_e32 v171, 0, v171, vcc
	v_cmp_eq_f32_e32 vcc, v172, v215
	v_exp_f32_e32 v172, v216
	v_add_f32_e32 v215, 0x42860000, v211
	v_fma_f32 v216, v213, |v215|, v239
	v_fmac_f32_e32 v216, 0x3fb8aa3b, v173
	v_med3_f32 v173, v215, v210, v212
	v_cndmask_b32_e32 v172, 0, v172, vcc
	v_cmp_eq_f32_e32 vcc, v173, v215
	v_exp_f32_e32 v173, v216
	v_add_f32_e32 v214, 0, v186
; __device__ __forceinline__ unsigned pk2(float lo, float hi) { return pg8::cvt_pk_bf16(lo, hi); }
; __device__ __forceinline__ void attention_item(LAS unsigned char* lds, const bf16* ZH, bf16* OP, float* LP, bf16* MIX, const float* qg, const float* kg, int item, int tid0) {
;     ...
;         if (blk + 1 < 48) att_load_q(qw, blk + 1);
;     ...
;           const int i = 16 * w + lr, rb = 16 * jt0 + 4 * lg - 64 - i, lo_i = -(i + B.qi0), hi_i = B.m - 1 - i - B.qi0;
;           const float rbf = (float)rb, LO = (float)(lo_i > -64 ? lo_i : -64), HI = (float)(hi_i < 64 ? hi_i : 64);
;           const float L2E = 1.4426950408889634f, sdl = sd * L2E, sml = smax * L2E;
; #pragma unroll
;           for (int t = 0; t < 10; ++t)
; #pragma unroll
;             for (int rr = 0; rr < 4; ++rr) { const float relf = rbf + (float)(16 * t + rr);
;                 const float x = __builtin_fmaf(sT[t][rr], L2E, __builtin_fmaf(-sdl, __builtin_fabsf(relf), -sml));
;                 const bool ok = __builtin_amdgcn_fmed3f(relf, LO, HI) == relf;
;                 const float p = ok ? __builtin_amdgcn_exp2f(x) : 0.f; sT[t][rr] = p; lsum += p; } }
;         bf16x8 pt[5];
; #pragma unroll
;         for (int k = 0; k < 5; ++k) { v4u o; o.x = pk2(sT[2 * k][0], sT[2 * k][1]); o.y = pk2(sT[2 * k][2], sT[2 * k][3]); o.z = pk2(sT[2 * k + 1][0], sT[2 * k + 1][1]); o.w = pk2(sT[2 * k + 1][2], sT[2 * k + 1][3]); pt[k] = __builtin_bit_cast(bf16x8, o); }
	v_add_f32_e32 v215, 0x42a00000, v211
	v_add_f32_e32 v214, v187, v214
	v_fma_f32 v216, v213, |v215|, v239
	v_add_f32_e32 v214, v188, v214
	v_fmac_f32_e32 v216, 0x3fb8aa3b, v166
	v_med3_f32 v166, v215, v210, v212
	v_add_f32_e32 v214, v189, v214
	v_cndmask_b32_e32 v173, 0, v173, vcc
	v_cmp_eq_f32_e32 vcc, v166, v215
	v_exp_f32_e32 v166, v216
	v_add_f32_e32 v214, v182, v214
	v_add_f32_e32 v215, 0x42a20000, v211
	v_add_f32_e32 v214, v183, v214
	v_fma_f32 v216, v213, |v215|, v239
	v_add_f32_e32 v214, v184, v214
	v_fmac_f32_e32 v216, 0x3fb8aa3b, v167
	v_med3_f32 v167, v215, v210, v212
	v_add_f32_e32 v214, v185, v214
	v_cndmask_b32_e32 v166, 0, v166, vcc
	v_cmp_eq_f32_e32 vcc, v167, v215
	v_exp_f32_e32 v167, v216
	v_add_f32_e32 v214, v178, v214
	v_add_f32_e32 v215, 0x42a40000, v211
	v_add_f32_e32 v214, v179, v214
	v_fma_f32 v216, v213, |v215|, v239
	v_add_f32_e32 v214, v180, v214
	v_fmac_f32_e32 v216, 0x3fb8aa3b, v168
	v_med3_f32 v168, v215, v210, v212
	v_add_f32_e32 v214, v181, v214
	v_cndmask_b32_e32 v167, 0, v167, vcc
	v_cmp_eq_f32_e32 vcc, v168, v215
	v_exp_f32_e32 v168, v216
	v_add_f32_e32 v214, v174, v214
	v_add_f32_e32 v215, 0x42a60000, v211
	v_add_f32_e32 v214, v175, v214
	v_fma_f32 v216, v213, |v215|, v239
	v_add_f32_e32 v214, v176, v214
	v_fmac_f32_e32 v216, 0x3fb8aa3b, v169
	v_med3_f32 v169, v215, v210, v212
	v_add_f32_e32 v214, v177, v214
	v_cndmask_b32_e32 v168, 0, v168, vcc
	v_cmp_eq_f32_e32 vcc, v169, v215
	v_exp_f32_e32 v169, v216
	v_add_f32_e32 v214, v170, v214
	v_add_f32_e32 v215, 0x42c00000, v211
	v_add_f32_e32 v214, v171, v214
	v_fma_f32 v216, v213, |v215|, v239
	v_add_f32_e32 v214, v172, v214
	v_fmac_f32_e32 v216, 0x3fb8aa3b, v162
	v_med3_f32 v162, v215, v210, v212
	v_add_f32_e32 v214, v173, v214
	v_cndmask_b32_e32 v169, 0, v169, vcc
	v_cmp_eq_f32_e32 vcc, v162, v215
	v_exp_f32_e32 v162, v216
	v_add_f32_e32 v214, v166, v214
	v_add_f32_e32 v214, v167, v214
	v_add_f32_e32 v214, v168, v214
	v_add_f32_e32 v214, v169, v214
	v_cndmask_b32_e32 v215, 0, v162, vcc
	v_add_f32_e32 v162, v215, v214
	v_add_f32_e32 v214, 0x42c20000, v211
	v_fma_f32 v216, v213, |v214|, v239
	v_fmac_f32_e32 v216, 0x3fb8aa3b, v163
	v_med3_f32 v163, v214, v210, v212
	v_cmp_eq_f32_e32 vcc, v163, v214
	v_exp_f32_e32 v163, v216
	v_add_u32_e32 v66, s45, v66
	v_lshl_or_b32 v66, v66, 8, v228
	global_load_dwordx4 v[114:117], v66, s[60:61]
	global_load_dwordx4 v[98:101], v66, s[60:61] offset:64
	global_load_dwordx4 v[74:77], v66, s[60:61] offset:128
	s_nop 0
	global_load_dwordx4 v[66:69], v66, s[60:61] offset:192
	v_cndmask_b32_e32 v214, 0, v163, vcc
	v_add_f32_e32 v163, 0x42c40000, v211
	v_fma_f32 v216, v213, |v163|, v239
	v_fmac_f32_e32 v216, 0x3fb8aa3b, v164
	v_med3_f32 v164, v163, v210, v212
	v_cmp_eq_f32_e32 vcc, v164, v163
	v_exp_f32_e32 v163, v216
	v_add_f32_e32 v162, v214, v162
	v_cvt_pk_bf16_f32 v186, v186, v187
	v_cvt_pk_bf16_f32 v187, v188, v189
	v_cndmask_b32_e32 v216, 0, v163, vcc
	v_add_f32_e32 v163, 0x42c60000, v211
	v_fma_f32 v164, v213, |v163|, v239
	v_fmac_f32_e32 v164, 0x3fb8aa3b, v165
	v_med3_f32 v165, v163, v210, v212
	v_cmp_eq_f32_e32 vcc, v165, v163
	v_exp_f32_e32 v163, v164
	v_add_f32_e32 v162, v216, v162
	v_cvt_pk_bf16_f32 v188, v182, v183
	v_cvt_pk_bf16_f32 v189, v184, v185
	v_cndmask_b32_e32 v217, 0, v163, vcc
	v_add_f32_e32 v163, 0x42e00000, v211
	v_fma_f32 v164, v213, |v163|, v239
	v_fmac_f32_e32 v164, 0x3fb8aa3b, v158
	v_med3_f32 v158, v163, v210, v212
	v_cmp_eq_f32_e32 vcc, v158, v163
	v_exp_f32_e32 v158, v164
	v_add_f32_e32 v162, v217, v162
	v_cndmask_b32_e32 v218, 0, v158, vcc
	v_add_f32_e32 v158, v218, v162
	v_add_f32_e32 v162, 0x42e20000, v211
	v_fma_f32 v163, v213, |v162|, v239
	v_fmac_f32_e32 v163, 0x3fb8aa3b, v159
	v_med3_f32 v159, v162, v210, v212
	v_cmp_eq_f32_e32 vcc, v159, v162
	v_exp_f32_e32 v159, v163
	s_nop 0
	v_cndmask_b32_e32 v219, 0, v159, vcc
	v_add_f32_e32 v159, 0x42e40000, v211
	v_fma_f32 v162, v213, |v159|, v239
	v_fmac_f32_e32 v162, 0x3fb8aa3b, v160
	v_med3_f32 v160, v159, v210, v212
	v_cmp_eq_f32_e32 vcc, v160, v159
	v_exp_f32_e32 v159, v162
	v_add_f32_e32 v158, v219, v158
	v_cvt_pk_bf16_f32 v162, v178, v179
	v_cvt_pk_bf16_f32 v163, v180, v181
	v_cndmask_b32_e32 v220, 0, v159, vcc
	v_add_f32_e32 v159, 0x42e60000, v211
	v_fma_f32 v160, v213, |v159|, v239
	v_fmac_f32_e32 v160, 0x3fb8aa3b, v161
	v_med3_f32 v161, v159, v210, v212
	v_cmp_eq_f32_e32 vcc, v161, v159
	v_exp_f32_e32 v159, v160
	v_add_f32_e32 v158, v220, v158
	v_cvt_pk_bf16_f32 v164, v174, v175
	v_cvt_pk_bf16_f32 v165, v176, v177
	v_cndmask_b32_e32 v221, 0, v159, vcc
	v_add_f32_e32 v159, 0x43000000, v211
	v_fma_f32 v160, v213, |v159|, v239
	v_fmac_f32_e32 v160, 0x3fb8aa3b, v154
	v_med3_f32 v154, v159, v210, v212
	v_cmp_eq_f32_e32 vcc, v154, v159
	v_exp_f32_e32 v154, v160
	v_add_f32_e32 v159, 0x43010000, v211
	v_fma_f32 v160, v213, |v159|, v239
	v_fmac_f32_e32 v160, 0x3fb8aa3b, v155
	v_med3_f32 v155, v159, v210, v212
	v_cndmask_b32_e32 v154, 0, v154, vcc
	v_cmp_eq_f32_e32 vcc, v155, v159
	v_exp_f32_e32 v155, v160
	v_add_f32_e32 v159, 0x43020000, v211
	v_fma_f32 v160, v213, |v159|, v239
	v_fmac_f32_e32 v160, 0x3fb8aa3b, v156
	v_med3_f32 v156, v159, v210, v212
	v_cndmask_b32_e32 v155, 0, v155, vcc
	v_cmp_eq_f32_e32 vcc, v156, v159
	v_exp_f32_e32 v156, v160
	v_add_f32_e32 v159, 0x43030000, v211
	v_fma_f32 v160, v213, |v159|, v239
	v_fmac_f32_e32 v160, 0x3fb8aa3b, v157
	v_med3_f32 v157, v159, v210, v212
	v_cndmask_b32_e32 v156, 0, v156, vcc
	v_cmp_eq_f32_e32 vcc, v157, v159
	v_exp_f32_e32 v157, v160
	v_add_f32_e32 v158, v221, v158
	v_add_f32_e32 v158, v154, v158
	v_add_f32_e32 v158, v155, v158
	v_add_f32_e32 v158, v156, v158
	v_cndmask_b32_e32 v157, 0, v157, vcc
; #define LAS __attribute__((address_space(3)))
; __device__ __forceinline__ unsigned pk2(float lo, float hi) { return pg8::cvt_pk_bf16(lo, hi); }
; #define MFMA16(a, b, c) __builtin_amdgcn_mfma_f32_16x16x32_bf16((a), (b), (c), 0, 0, 0)
; __device__ __forceinline__ bf16x8 ds_tr2(LAS unsigned char* p, int rstride) { const s16x4 a = ds_tr(p), b = ds_tr(p + 16 * rstride); bf16x8 r; r[0] = a[0]; r[1] = a[1]; r[2] = a[2]; r[3] = a[3]; r[4] = b[0]; r[5] = b[1]; r[6] = b[2]; r[7] = b[3]; return r; }
; __device__ __forceinline__ void attention_item(LAS unsigned char* lds, const bf16* ZH, bf16* OP, float* LP, bf16* MIX, const float* qg, const float* kg, int item, int tid0) {
;     ...
;             for (int rr = 0; rr < 4; ++rr) { const float relf = rbf + (float)(16 * t + rr);
;                 const float x = __builtin_fmaf(sT[t][rr], L2E, __builtin_fmaf(-sdl, __builtin_fabsf(relf), -sml));
;                 const bool ok = __builtin_amdgcn_fmed3f(relf, LO, HI) == relf;
;                 const float p = ok ? __builtin_amdgcn_exp2f(x) : 0.f; sT[t][rr] = p; lsum += p; } }
;         bf16x8 pt[5];
; #pragma unroll
;         for (int k = 0; k < 5; ++k) { v4u o; o.x = pk2(sT[2 * k][0], sT[2 * k][1]); o.y = pk2(sT[2 * k][2], sT[2 * k][3]); o.z = pk2(sT[2 * k + 1][0], sT[2 * k + 1][1]); o.w = pk2(sT[2 * k + 1][2], sT[2 * k + 1][3]); pt[k] = __builtin_bit_cast(bf16x8, o); }
;         f32x4 o[8];
;         { LAS unsigned char* trp = lds + A_V + (4 * lg + ((l & 15) >> 2)) * RSB + (l & 3) * 8;
; #pragma unroll
;           for (int e = 0; e < 8; ++e) o[e] = (f32x4){0.f, 0.f, 0.f, 0.f};
; #pragma unroll
;           for (int k = 0; k < 5; ++k) { const int rowb = (16 * jt0 + 32 * k + off) & 255;
; #pragma unroll
;             for (int e = 0; e < 8; ++e) { const bf16x8 vf = ds_tr2(trp + rowb * RSB + (16 * e) * 2, RSB); o[e] = MFMA16(vf, pt[k], o[e]);
	v_add_f32_e32 v222, v157, v158
	v_add_f32_e32 v158, 0x43100000, v211
	v_fma_f32 v159, v213, |v158|, v239
	v_fmac_f32_e32 v159, 0x3fb8aa3b, v150
	v_med3_f32 v150, v158, v210, v212
	v_cmp_eq_f32_e32 vcc, v150, v158
	v_exp_f32_e32 v150, v159
	s_nop 0
	v_cndmask_b32_e32 v223, 0, v150, vcc
	v_add_f32_e32 v150, 0x43110000, v211
	v_fma_f32 v158, v213, |v150|, v239
	v_fmac_f32_e32 v158, 0x3fb8aa3b, v151
	v_med3_f32 v151, v150, v210, v212
	v_cmp_eq_f32_e32 vcc, v151, v150
	v_exp_f32_e32 v150, v158
	v_cvt_pk_bf16_f32 v158, v170, v171
	v_cvt_pk_bf16_f32 v159, v172, v173
	v_cvt_pk_bf16_f32 v160, v166, v167
	v_add_f32_e32 v166, v223, v222
	v_cndmask_b32_e32 v224, 0, v150, vcc
	v_add_f32_e32 v150, 0x43120000, v211
	v_fma_f32 v151, v213, |v150|, v239
	v_fmac_f32_e32 v151, 0x3fb8aa3b, v152
	v_med3_f32 v152, v150, v210, v212
	v_cmp_eq_f32_e32 vcc, v152, v150
	v_exp_f32_e32 v150, v151
	v_add_f32_e32 v166, v224, v166
	v_lshlrev_b32_e32 v167, 3, v209
	v_and_b32_e32 v167, 24, v167
	v_cndmask_b32_e32 v225, 0, v150, vcc
	v_add_f32_e32 v150, 0x43130000, v211
	v_fma_f32 v151, v213, |v150|, v239
	v_fmac_f32_e32 v151, 0x3fb8aa3b, v153
	v_med3_f32 v152, v150, v210, v212
	v_add_f32_e32 v182, v225, v166
	v_lshrrev_b32_e32 v166, 2, v2
	v_cmp_eq_f32_e32 vcc, v152, v150
	v_exp_f32_e32 v150, v151
	v_or_b32_e32 v166, v208, v166
	v_mul_u32_u24_e32 v166, 0x120, v166
	v_add3_u32 v166, s92, v166, v167
	v_mad_u32_u24 v167, v206, s74, v166
	v_cndmask_b32_e32 v210, 0, v150, vcc
	v_cvt_pk_bf16_f32 v161, v168, v169
	v_cvt_pk_bf16_f32 v150, v215, v214
	v_cvt_pk_bf16_f32 v151, v216, v217
	v_cvt_pk_bf16_f32 v152, v218, v219
	v_cvt_pk_bf16_f32 v153, v220, v221
	v_cvt_pk_bf16_f32 v154, v154, v155
	v_cvt_pk_bf16_f32 v155, v156, v157
	v_cvt_pk_bf16_f32 v156, v223, v224
	v_cvt_pk_bf16_f32 v157, v225, v210
	ds_read_b64_tr_b16 v[170:171], v167 offset:4608
	ds_read_b64_tr_b16 v[168:169], v167
	ds_read_b64_tr_b16 v[172:173], v167 offset:32
	ds_read_b64_tr_b16 v[174:175], v167 offset:4640
	ds_read_b64_tr_b16 v[176:177], v167 offset:64
	ds_read_b64_tr_b16 v[178:179], v167 offset:4672
	ds_read_b64_tr_b16 v[212:213], v167 offset:96
	ds_read_b64_tr_b16 v[214:215], v167 offset:4704
	s_waitcnt lgkmcnt(6)
	v_mfma_f32_16x16x32_bf16 v[168:171], v[168:171], v[186:189], 0
	s_waitcnt lgkmcnt(4)
	v_mfma_f32_16x16x32_bf16 v[172:175], v[172:175], v[186:189], 0
	s_waitcnt lgkmcnt(2)
	v_mfma_f32_16x16x32_bf16 v[176:179], v[176:179], v[186:189], 0
	s_waitcnt lgkmcnt(0)
	v_mfma_f32_16x16x32_bf16 v[212:215], v[212:215], v[186:189], 0
	ds_read_b64_tr_b16 v[216:217], v167 offset:128
	ds_read_b64_tr_b16 v[218:219], v167 offset:4736
	ds_read_b64_tr_b16 v[222:223], v167 offset:4768
	ds_read_b64_tr_b16 v[220:221], v167 offset:160
	ds_read_b64_tr_b16 v[240:241], v167 offset:192
	ds_read_b64_tr_b16 v[244:245], v167 offset:224
	ds_read_b64_tr_b16 v[242:243], v167 offset:4800
	ds_read_b64_tr_b16 v[246:247], v167 offset:4832
	s_waitcnt lgkmcnt(4)
	v_mfma_f32_16x16x32_bf16 v[220:223], v[220:223], v[186:189], 0
	s_waitcnt lgkmcnt(1)
	v_mfma_f32_16x16x32_bf16 v[240:243], v[240:243], v[186:189], 0
	v_mfma_f32_16x16x32_bf16 v[216:219], v[216:219], v[186:189], 0
	s_waitcnt lgkmcnt(0)
	v_mfma_f32_16x16x32_bf16 v[184:187], v[244:247], v[186:189], 0
	v_add_u32_e32 v167, 32, v207
	v_and_b32_e32 v167, 0xe0, v167
	v_mad_u32_u24 v167, v167, s74, v166
	ds_read_b64_tr_b16 v[246:247], v167 offset:4608
	ds_read_b64_tr_b16 v[244:245], v167
	ds_read_b64_tr_b16 v[248:249], v167 offset:32
	ds_read_b64_tr_b16 v[250:251], v167 offset:4640
	s_waitcnt lgkmcnt(2)
	v_mfma_f32_16x16x32_bf16 v[168:171], v[244:247], v[162:165], v[168:171]
	ds_read_b64_tr_b16 v[244:245], v167 offset:64
	ds_read_b64_tr_b16 v[246:247], v167 offset:4672
	s_waitcnt lgkmcnt(0)
	v_mfma_f32_16x16x32_bf16 v[176:179], v[244:247], v[162:165], v[176:179]
	ds_read_b64_tr_b16 v[244:245], v167 offset:96
	ds_read_b64_tr_b16 v[246:247], v167 offset:4704
	v_mfma_f32_16x16x32_bf16 v[172:175], v[248:251], v[162:165], v[172:175]
	s_waitcnt lgkmcnt(0)
	v_mfma_f32_16x16x32_bf16 v[212:215], v[244:247], v[162:165], v[212:215]
	ds_read_b64_tr_b16 v[246:247], v167 offset:4736
	ds_read_b64_tr_b16 v[244:245], v167 offset:128
	ds_read_b64_tr_b16 v[248:249], v167 offset:160
	ds_read_b64_tr_b16 v[250:251], v167 offset:4768
	s_waitcnt lgkmcnt(2)
	v_mfma_f32_16x16x32_bf16 v[216:219], v[244:247], v[162:165], v[216:219]
	ds_read_b64_tr_b16 v[244:245], v167 offset:192
	ds_read_b64_tr_b16 v[246:247], v167 offset:4800
	s_waitcnt lgkmcnt(0)
	v_mfma_f32_16x16x32_bf16 v[240:243], v[244:247], v[162:165], v[240:243]
	ds_read_b64_tr_b16 v[244:245], v167 offset:224
	ds_read_b64_tr_b16 v[246:247], v167 offset:4832
	v_mfma_f32_16x16x32_bf16 v[220:223], v[248:251], v[162:165], v[220:223]
	s_waitcnt lgkmcnt(0)
	v_mfma_f32_16x16x32_bf16 v[162:165], v[244:247], v[162:165], v[184:187]
	v_add_u32_e32 v167, 64, v207
	v_and_b32_e32 v167, 0xe0, v167
	v_mad_u32_u24 v167, v167, s74, v166
	ds_read_b64_tr_b16 v[186:187], v167 offset:4608
	ds_read_b64_tr_b16 v[184:185], v167
	ds_read_b64_tr_b16 v[244:245], v167 offset:32
	ds_read_b64_tr_b16 v[246:247], v167 offset:4640
	s_waitcnt lgkmcnt(2)
	v_mfma_f32_16x16x32_bf16 v[168:171], v[184:187], v[158:161], v[168:171]
	ds_read_b64_tr_b16 v[184:185], v167 offset:64
	ds_read_b64_tr_b16 v[186:187], v167 offset:4672
	s_waitcnt lgkmcnt(0)
	v_mfma_f32_16x16x32_bf16 v[176:179], v[184:187], v[158:161], v[176:179]
	ds_read_b64_tr_b16 v[184:185], v167 offset:96
	ds_read_b64_tr_b16 v[186:187], v167 offset:4704
	v_mfma_f32_16x16x32_bf16 v[172:175], v[244:247], v[158:161], v[172:175]
	s_waitcnt lgkmcnt(0)
; #define GAS __attribute__((address_space(1)))
; __device__ __forceinline__ unsigned pk2(float lo, float hi) { return pg8::cvt_pk_bf16(lo, hi); }
; #define MFMA16(a, b, c) __builtin_amdgcn_mfma_f32_16x16x32_bf16((a), (b), (c), 0, 0, 0)
; __device__ __forceinline__ bf16x8 ds_tr2(LAS unsigned char* p, int rstride) { const s16x4 a = ds_tr(p), b = ds_tr(p + 16 * rstride); bf16x8 r; r[0] = a[0]; r[1] = a[1]; r[2] = a[2]; r[3] = a[3]; r[4] = b[0]; r[5] = b[1]; r[6] = b[2]; r[7] = b[3]; return r; }
; __device__ __forceinline__ void attention_item(LAS unsigned char* lds, const bf16* ZH, bf16* OP, float* LP, bf16* MIX, const float* qg, const float* kg, int item, int tid0) {
;     ...
;           for (int k = 0; k < 5; ++k) { const int rowb = (16 * jt0 + 32 * k + off) & 255;
; #pragma unroll
;             for (int e = 0; e < 8; ++e) { const bf16x8 vf = ds_tr2(trp + rowb * RSB + (16 * e) * 2, RSB); o[e] = MFMA16(vf, pt[k], o[e]);
;                 if (e == 3) __builtin_amdgcn_sched_barrier(0); }
;             __builtin_amdgcn_sched_barrier(0); } }
;         lsum += __shfl_xor(lsum, 16); lsum += __shfl_xor(lsum, 32);
;         const int row = rowbase + B.r + B.d * (B.qi0 + 16 * w + lr);
;         if (B.dsh != 0) {
;             const int pb = B.dsh == 4 ? 0 : 1;
;             bf16* op = OP + ((size_t)pb * M + row) * 2048 + h * HD + 4 * lg;
; #pragma unroll
;             for (int e = 0; e < 8; ++e) { v2u ov; ov.x = pk2(o[e][0], o[e][1]); ov.y = pk2(o[e][2], o[e][3]); *(GAS v2u*)(op + 16 * e) = ov; }
;             if (lg == 0) LP[((size_t)pb * NH + h) * M + row] = lsum;
	v_mfma_f32_16x16x32_bf16 v[184:187], v[184:187], v[158:161], v[212:215]
	s_nop 2
	ds_read_b64_tr_b16 v[214:215], v167 offset:4736
	ds_read_b64_tr_b16 v[212:213], v167 offset:128
	ds_read_b64_tr_b16 v[244:245], v167 offset:160
	ds_read_b64_tr_b16 v[246:247], v167 offset:4768
	s_waitcnt lgkmcnt(2)
	v_mfma_f32_16x16x32_bf16 v[212:215], v[212:215], v[158:161], v[216:219]
	s_waitcnt lgkmcnt(0)
	v_mfma_f32_16x16x32_bf16 v[216:219], v[244:247], v[158:161], v[220:223]
	s_nop 2
	ds_read_b64_tr_b16 v[220:221], v167 offset:192
	ds_read_b64_tr_b16 v[222:223], v167 offset:4800
	s_waitcnt lgkmcnt(0)
	v_mfma_f32_16x16x32_bf16 v[220:223], v[220:223], v[158:161], v[240:243]
	s_nop 2
	ds_read_b64_tr_b16 v[240:241], v167 offset:224
	ds_read_b64_tr_b16 v[242:243], v167 offset:4832
	s_waitcnt lgkmcnt(0)
	v_mfma_f32_16x16x32_bf16 v[158:161], v[240:243], v[158:161], v[162:165]
	s_nop 2
	v_add_u32_e32 v162, 0x60, v207
	v_and_b32_e32 v162, 0xe0, v162
	v_mad_u32_u24 v167, v162, s74, v166
	ds_read_b64_tr_b16 v[164:165], v167 offset:4608
	ds_read_b64_tr_b16 v[162:163], v167
	ds_read_b64_tr_b16 v[240:241], v167 offset:32
	ds_read_b64_tr_b16 v[242:243], v167 offset:4640
	s_waitcnt lgkmcnt(2)
	v_mfma_f32_16x16x32_bf16 v[162:165], v[162:165], v[150:153], v[168:171]
	s_waitcnt lgkmcnt(0)
	v_mfma_f32_16x16x32_bf16 v[168:171], v[240:243], v[150:153], v[172:175]
	s_nop 2
	ds_read_b64_tr_b16 v[172:173], v167 offset:64
	ds_read_b64_tr_b16 v[174:175], v167 offset:4672
	s_waitcnt lgkmcnt(0)
	v_mfma_f32_16x16x32_bf16 v[240:243], v[172:175], v[150:153], v[176:179]
	ds_read_b64_tr_b16 v[172:173], v167 offset:96
	ds_read_b64_tr_b16 v[174:175], v167 offset:4704
	s_waitcnt lgkmcnt(0)
	v_mfma_f32_16x16x32_bf16 v[184:187], v[172:175], v[150:153], v[184:187]
	ds_read_b64_tr_b16 v[174:175], v167 offset:4736
	ds_read_b64_tr_b16 v[172:173], v167 offset:128
	ds_read_b64_tr_b16 v[176:177], v167 offset:160
	ds_read_b64_tr_b16 v[178:179], v167 offset:4768
	s_waitcnt lgkmcnt(2)
	v_mfma_f32_16x16x32_bf16 v[212:215], v[172:175], v[150:153], v[212:215]
	ds_read_b64_tr_b16 v[172:173], v167 offset:192
	ds_read_b64_tr_b16 v[174:175], v167 offset:4800
	s_waitcnt lgkmcnt(0)
	v_mfma_f32_16x16x32_bf16 v[220:223], v[172:175], v[150:153], v[220:223]
	ds_read_b64_tr_b16 v[172:173], v167 offset:224
	ds_read_b64_tr_b16 v[174:175], v167 offset:4832
	v_mfma_f32_16x16x32_bf16 v[216:219], v[176:179], v[150:153], v[216:219]
	s_waitcnt lgkmcnt(0)
	v_mfma_f32_16x16x32_bf16 v[244:247], v[172:175], v[150:153], v[158:161]
	v_xor_b32_e32 v150, 0x80, v206
	v_mad_u32_u24 v183, v150, s74, v166
	ds_read_b64_tr_b16 v[152:153], v183 offset:4608
	ds_read_b64_tr_b16 v[150:151], v183
	ds_read_b64_tr_b16 v[158:159], v183 offset:32
	ds_read_b64_tr_b16 v[160:161], v183 offset:4640
	s_waitcnt lgkmcnt(2)
	v_mfma_f32_16x16x32_bf16 v[178:181], v[150:153], v[154:157], v[162:165]
	ds_read_b64_tr_b16 v[150:151], v183 offset:64
	ds_read_b64_tr_b16 v[152:153], v183 offset:4672
	s_waitcnt lgkmcnt(2)
	v_mfma_f32_16x16x32_bf16 v[174:177], v[158:161], v[154:157], v[168:171]
	s_waitcnt lgkmcnt(0)
	v_mfma_f32_16x16x32_bf16 v[166:169], v[150:153], v[154:157], v[240:243]
	ds_read_b64_tr_b16 v[150:151], v183 offset:96
	ds_read_b64_tr_b16 v[152:153], v183 offset:4704
	s_waitcnt lgkmcnt(0)
	v_mfma_f32_16x16x32_bf16 v[170:173], v[150:153], v[154:157], v[184:187]
	ds_read_b64_tr_b16 v[152:153], v183 offset:4736
	ds_read_b64_tr_b16 v[150:151], v183 offset:128
	ds_read_b64_tr_b16 v[158:159], v183 offset:160
	ds_read_b64_tr_b16 v[160:161], v183 offset:4768
	s_waitcnt lgkmcnt(2)
	v_mfma_f32_16x16x32_bf16 v[162:165], v[150:153], v[154:157], v[212:215]
	ds_read_b64_tr_b16 v[150:151], v183 offset:192
	ds_read_b64_tr_b16 v[152:153], v183 offset:4800
	ds_read_b64_tr_b16 v[184:185], v183 offset:224
	ds_read_b64_tr_b16 v[186:187], v183 offset:4832
	s_waitcnt lgkmcnt(4)
	v_mfma_f32_16x16x32_bf16 v[158:161], v[158:161], v[154:157], v[216:219]
	s_waitcnt lgkmcnt(2)
	v_mfma_f32_16x16x32_bf16 v[150:153], v[150:153], v[154:157], v[220:223]
	s_waitcnt lgkmcnt(0)
	v_mfma_f32_16x16x32_bf16 v[154:157], v[184:187], v[154:157], v[244:247]
	v_add_f32_e32 v182, v210, v182
	ds_bpermute_b32 v183, v205, v182
	v_or_b32_e32 v2, s34, v2
	v_add_lshl_u32 v2, v2, v5, s42
	s_add_i32 s28, s28, s20
	v_add_u32_e32 v220, s28, v2
	s_waitcnt lgkmcnt(0)
	v_add_f32_e32 v182, v182, v183
	ds_bpermute_b32 v183, v226, v182
	s_mov_b64 s[34:35], -1
	s_andn2_b64 vcc, exec, s[54:55]
	v_ashrrev_i32_e32 v221, 31, v220
	v_lshlrev_b32_e32 v2, 1, v208
	s_waitcnt lgkmcnt(0)
	v_add_f32_e32 v240, v182, v183
	s_cbranch_vccnz .LBB0_396
	s_and_b64 s[34:35], exec, s[40:41]
	s_cselect_b32 s28, 0, 0x4000
	v_lshl_add_u64 v[182:183], s[28:29], 0, v[220:221]
	v_lshlrev_b64 v[182:183], 12, v[182:183]
	v_lshl_add_u64 v[182:183], s[72:73], 0, v[182:183]
	v_and_b32_e32 v184, 16, v0
	v_lshrrev_b32_e32 v185, 1, v184
	v_add3_u32 v2, v2, v184, v185
	v_lshl_add_u64 v[182:183], v[182:183], 0, v[2:3]
	v_cvt_pk_bf16_f32 v178, v178, v179
	v_cvt_pk_bf16_f32 v179, v180, v181
	v_cvt_pk_bf16_f32 v180, v174, v175
	v_cvt_pk_bf16_f32 v181, v176, v177
	s_nop 1
	v_permlane16_swap_b32_e32 v178, v180
	v_permlane16_swap_b32_e32 v179, v181
	global_store_dwordx4 v[182:183], v[178:181], off
	v_cvt_pk_bf16_f32 v166, v166, v167
	v_cvt_pk_bf16_f32 v167, v168, v169
	v_cvt_pk_bf16_f32 v168, v170, v171
	v_cvt_pk_bf16_f32 v169, v172, v173
	s_nop 1
	v_permlane16_swap_b32_e32 v166, v168
	v_permlane16_swap_b32_e32 v167, v169
	global_store_dwordx4 v[182:183], v[166:169], off offset:64
	v_cvt_pk_bf16_f32 v162, v162, v163
	v_cvt_pk_bf16_f32 v163, v164, v165
	v_cvt_pk_bf16_f32 v164, v158, v159
	v_cvt_pk_bf16_f32 v165, v160, v161
	s_nop 1
	v_permlane16_swap_b32_e32 v162, v164
	v_permlane16_swap_b32_e32 v163, v165
	global_store_dwordx4 v[182:183], v[162:165], off offset:128
	v_cvt_pk_bf16_f32 v150, v150, v151
	v_cvt_pk_bf16_f32 v151, v152, v153
	v_cvt_pk_bf16_f32 v152, v154, v155
	v_cvt_pk_bf16_f32 v153, v156, v157
	s_nop 1
	v_permlane16_swap_b32_e32 v150, v152
	v_permlane16_swap_b32_e32 v151, v153
	global_store_dwordx4 v[182:183], v[150:153], off offset:192
	v_cmp_eq_u32_e32 vcc, 0, v4
	s_and_saveexec_b64 s[34:35], vcc
	s_cbranch_execz .LBB0_389
	s_and_b64 s[54:55], exec, s[40:41]
	s_cselect_b32 s28, 0, 16
	s_or_b32 s28, s28, s46
	s_lshl_b32 s28, s28, 16
	s_add_u32 s54, s21, s28
	s_addc_u32 s55, s65, 0
	v_lshl_add_u64 v[4:5], v[220:221], 2, s[54:55]
	global_store_dword v[4:5], v240, off

; __device__ __forceinline__ void attention_item(LAS unsigned char* lds, const bf16* ZH, bf16* OP, float* LP, bf16* MIX, const float* qg, const float* kg, int item, int tid0) {
;     ...
;           const int i = 16 * w + lr, rb = 16 * jt0 + 4 * lg - 64 - i, lo_i = -(i + B.qi0), hi_i = B.m - 1 - i - B.qi0;
;           const float rbf = (float)rb, LO = (float)(lo_i > -64 ? lo_i : -64), HI = (float)(hi_i < 64 ? hi_i : 64);
;           const float L2E = 1.4426950408889634f, sdl = sd * L2E, sml = smax * L2E;
; #pragma unroll
;           for (int t = 0; t < 10; ++t)
; #pragma unroll
;             for (int rr = 0; rr < 4; ++rr) { const float relf = rbf + (float)(16 * t + rr);
;                 const float x = __builtin_fmaf(sT[t][rr], L2E, __builtin_fmaf(-sdl, __builtin_fabsf(relf), -sml));
;                 const bool ok = __builtin_amdgcn_fmed3f(relf, LO, HI) == relf;
;                 const float p = ok ? __builtin_amdgcn_exp2f(x) : 0.f; sT[t][rr] = p; lsum += p; } }
.LBB0_438:
	s_waitcnt lgkmcnt(0)
	s_lshl_b32 s34, 1, s42
	v_cvt_f32_ubyte0_e32 v160, s34
	v_mul_f32_e32 v165, v229, v160
	s_lshr_b32 s34, s47, s42
	v_lshlrev_b32_e32 v160, 2, v4
	s_lshr_b32 s35, s64, s42
	s_add_i32 s34, s55, s34
	v_or_b32_e32 v163, v5, v2
	v_add_u32_e32 v162, v162, v160
	v_sub_u32_e32 v162, v162, v163
	v_add_u32_e32 v164, s34, v163
	s_sub_i32 s35, s35, s34
	v_subrev_u32_e32 v162, 64, v162
	v_sub_u32_e32 v164, 0, v164
	v_xad_u32 v166, v163, -1, s35
	v_cvt_f32_i32_e32 v163, v162
	v_max_i32_e32 v162, 0xffffffc0, v164
	v_min_i32_e32 v164, 64, v166
	v_cvt_f32_i32_e32 v162, v162
	v_cvt_f32_i32_e32 v164, v164
	v_mul_f32_e32 v165, 0xbfb8aa3b, v165
	v_fma_f32 v166, v165, |v163|, v239
	v_fmac_f32_e32 v166, 0x3fb8aa3b, v154
	v_med3_f32 v154, v163, v162, v164
	v_cmp_eq_f32_e32 vcc, v154, v163
	v_exp_f32_e32 v154, v166
	v_add_f32_e32 v167, 1.0, v163
	v_fma_f32 v168, v165, |v167|, v239
	v_fmac_f32_e32 v168, 0x3fb8aa3b, v155
	v_med3_f32 v155, v167, v162, v164
	v_cndmask_b32_e32 v154, 0, v154, vcc
	v_cmp_eq_f32_e32 vcc, v155, v167
	v_exp_f32_e32 v155, v168
	v_add_f32_e32 v167, 2.0, v163
	v_fma_f32 v168, v165, |v167|, v239
	v_fmac_f32_e32 v168, 0x3fb8aa3b, v156
	v_med3_f32 v156, v167, v162, v164
	v_cndmask_b32_e32 v155, 0, v155, vcc
	v_cmp_eq_f32_e32 vcc, v156, v167
	v_exp_f32_e32 v156, v168
	v_add_f32_e32 v167, 0x40400000, v163
	v_fma_f32 v168, v165, |v167|, v239
	v_fmac_f32_e32 v168, 0x3fb8aa3b, v157
	v_med3_f32 v157, v167, v162, v164
	v_cndmask_b32_e32 v156, 0, v156, vcc
	v_cmp_eq_f32_e32 vcc, v157, v167
	v_exp_f32_e32 v157, v168
	v_add_f32_e32 v167, 0x41800000, v163
	v_fma_f32 v168, v165, |v167|, v239
	v_fmac_f32_e32 v168, 0x3fb8aa3b, v150
	v_med3_f32 v150, v167, v162, v164
	v_cndmask_b32_e32 v157, 0, v157, vcc
	v_cmp_eq_f32_e32 vcc, v150, v167
	v_exp_f32_e32 v150, v168
	v_add_f32_e32 v167, 0x41880000, v163
	v_fma_f32 v168, v165, |v167|, v239
	v_fmac_f32_e32 v168, 0x3fb8aa3b, v151
	v_med3_f32 v151, v167, v162, v164
	v_cndmask_b32_e32 v150, 0, v150, vcc
	v_cmp_eq_f32_e32 vcc, v151, v167
	v_exp_f32_e32 v151, v168
	v_add_f32_e32 v167, 0x41900000, v163
	v_fma_f32 v168, v165, |v167|, v239
	v_fmac_f32_e32 v168, 0x3fb8aa3b, v152
	v_med3_f32 v152, v167, v162, v164
	v_cndmask_b32_e32 v151, 0, v151, vcc
	v_cmp_eq_f32_e32 vcc, v152, v167
	v_exp_f32_e32 v152, v168
	v_add_f32_e32 v167, 0x41980000, v163
	v_fma_f32 v168, v165, |v167|, v239
	v_fmac_f32_e32 v168, 0x3fb8aa3b, v153
	v_med3_f32 v153, v167, v162, v164
	v_cndmask_b32_e32 v152, 0, v152, vcc
	v_cmp_eq_f32_e32 vcc, v153, v167
	v_exp_f32_e32 v153, v168
	v_add_f32_e32 v167, 0x42000000, v163
	v_fma_f32 v168, v165, |v167|, v239
	v_fmac_f32_e32 v168, 0x3fb8aa3b, v146
	v_med3_f32 v146, v167, v162, v164
	v_cndmask_b32_e32 v153, 0, v153, vcc
	v_cmp_eq_f32_e32 vcc, v146, v167
	v_exp_f32_e32 v146, v168
	v_add_f32_e32 v167, 0x42040000, v163
	v_fma_f32 v168, v165, |v167|, v239
	v_fmac_f32_e32 v168, 0x3fb8aa3b, v147
	v_med3_f32 v147, v167, v162, v164
	v_cndmask_b32_e32 v146, 0, v146, vcc
	v_cmp_eq_f32_e32 vcc, v147, v167
	v_exp_f32_e32 v147, v168
	v_add_f32_e32 v167, 0x42080000, v163
	v_fma_f32 v168, v165, |v167|, v239
	v_fmac_f32_e32 v168, 0x3fb8aa3b, v148
	v_med3_f32 v148, v167, v162, v164
	v_cndmask_b32_e32 v147, 0, v147, vcc
	v_cmp_eq_f32_e32 vcc, v148, v167
	v_exp_f32_e32 v148, v168
	v_add_f32_e32 v167, 0x420c0000, v163
	v_fma_f32 v168, v165, |v167|, v239
	v_fmac_f32_e32 v168, 0x3fb8aa3b, v149
	v_med3_f32 v149, v167, v162, v164
	v_cndmask_b32_e32 v148, 0, v148, vcc
	v_cmp_eq_f32_e32 vcc, v149, v167
	v_exp_f32_e32 v149, v168
	v_add_f32_e32 v167, 0x42400000, v163
	v_fma_f32 v168, v165, |v167|, v239
	v_fmac_f32_e32 v168, 0x3fb8aa3b, v142
	v_med3_f32 v142, v167, v162, v164
	v_cndmask_b32_e32 v149, 0, v149, vcc
	v_cmp_eq_f32_e32 vcc, v142, v167
	v_exp_f32_e32 v142, v168
	v_add_f32_e32 v167, 0x42440000, v163
	v_fma_f32 v168, v165, |v167|, v239
	v_fmac_f32_e32 v168, 0x3fb8aa3b, v143
	v_med3_f32 v143, v167, v162, v164
	v_cndmask_b32_e32 v142, 0, v142, vcc
	v_cmp_eq_f32_e32 vcc, v143, v167
	v_exp_f32_e32 v143, v168
	v_add_f32_e32 v167, 0x42480000, v163
	v_fma_f32 v168, v165, |v167|, v239
	v_fmac_f32_e32 v168, 0x3fb8aa3b, v144
	v_med3_f32 v144, v167, v162, v164
	v_cndmask_b32_e32 v143, 0, v143, vcc
	v_cmp_eq_f32_e32 vcc, v144, v167
	v_exp_f32_e32 v144, v168
	v_add_f32_e32 v167, 0x424c0000, v163
	v_fma_f32 v168, v165, |v167|, v239
	v_fmac_f32_e32 v168, 0x3fb8aa3b, v145
	v_med3_f32 v145, v167, v162, v164
	v_cndmask_b32_e32 v144, 0, v144, vcc
	v_cmp_eq_f32_e32 vcc, v145, v167
	v_exp_f32_e32 v145, v168
	v_add_f32_e32 v167, 0x42800000, v163
	v_fma_f32 v168, v165, |v167|, v239
	v_fmac_f32_e32 v168, 0x3fb8aa3b, v138
	v_med3_f32 v138, v167, v162, v164
	v_cndmask_b32_e32 v145, 0, v145, vcc
	v_cmp_eq_f32_e32 vcc, v138, v167
	v_exp_f32_e32 v138, v168
	v_add_f32_e32 v167, 0x42820000, v163
	v_fma_f32 v168, v165, |v167|, v239
	v_fmac_f32_e32 v168, 0x3fb8aa3b, v139
	v_med3_f32 v139, v167, v162, v164
	v_cndmask_b32_e32 v138, 0, v138, vcc
	v_cmp_eq_f32_e32 vcc, v139, v167
	v_exp_f32_e32 v139, v168
	v_add_f32_e32 v167, 0x42840000, v163
	v_fma_f32 v168, v165, |v167|, v239
	v_fmac_f32_e32 v168, 0x3fb8aa3b, v140
	v_med3_f32 v140, v167, v162, v164
	v_cndmask_b32_e32 v139, 0, v139, vcc
	v_cmp_eq_f32_e32 vcc, v140, v167
	v_exp_f32_e32 v140, v168
	v_add_f32_e32 v167, 0x42860000, v163
	v_fma_f32 v168, v165, |v167|, v239
	v_fmac_f32_e32 v168, 0x3fb8aa3b, v141
	v_med3_f32 v141, v167, v162, v164
	v_cndmask_b32_e32 v140, 0, v140, vcc
	v_cmp_eq_f32_e32 vcc, v141, v167
	v_exp_f32_e32 v141, v168
	v_add_f32_e32 v166, 0, v154
	v_add_f32_e32 v167, 0x42a00000, v163
	v_add_f32_e32 v166, v155, v166
	v_fma_f32 v168, v165, |v167|, v239
; __device__ __forceinline__ unsigned pk2(float lo, float hi) { return pg8::cvt_pk_bf16(lo, hi); }
; __device__ __forceinline__ void attention_item(LAS unsigned char* lds, const bf16* ZH, bf16* OP, float* LP, bf16* MIX, const float* qg, const float* kg, int item, int tid0) {
;     ...
;           const int i = 16 * w + lr, rb = 16 * jt0 + 4 * lg - 64 - i, lo_i = -(i + B.qi0), hi_i = B.m - 1 - i - B.qi0;
;           const float rbf = (float)rb, LO = (float)(lo_i > -64 ? lo_i : -64), HI = (float)(hi_i < 64 ? hi_i : 64);
;           const float L2E = 1.4426950408889634f, sdl = sd * L2E, sml = smax * L2E;
; #pragma unroll
;           for (int t = 0; t < 10; ++t)
; #pragma unroll
;             for (int rr = 0; rr < 4; ++rr) { const float relf = rbf + (float)(16 * t + rr);
;                 const float x = __builtin_fmaf(sT[t][rr], L2E, __builtin_fmaf(-sdl, __builtin_fabsf(relf), -sml));
;                 const bool ok = __builtin_amdgcn_fmed3f(relf, LO, HI) == relf;
;                 const float p = ok ? __builtin_amdgcn_exp2f(x) : 0.f; sT[t][rr] = p; lsum += p; } }
;         bf16x8 pt[5];
; #pragma unroll
;         for (int k = 0; k < 5; ++k) { v4u o; o.x = pk2(sT[2 * k][0], sT[2 * k][1]); o.y = pk2(sT[2 * k][2], sT[2 * k][3]); o.z = pk2(sT[2 * k + 1][0], sT[2 * k + 1][1]); o.w = pk2(sT[2 * k + 1][2], sT[2 * k + 1][3]); pt[k] = __builtin_bit_cast(bf16x8, o); }
	v_add_f32_e32 v166, v156, v166
	v_fmac_f32_e32 v168, 0x3fb8aa3b, v134
	v_med3_f32 v134, v167, v162, v164
	v_add_f32_e32 v166, v157, v166
	v_cndmask_b32_e32 v141, 0, v141, vcc
	v_cmp_eq_f32_e32 vcc, v134, v167
	v_exp_f32_e32 v134, v168
	v_add_f32_e32 v166, v150, v166
	v_add_f32_e32 v167, 0x42a20000, v163
	v_add_f32_e32 v166, v151, v166
	v_fma_f32 v168, v165, |v167|, v239
	v_add_f32_e32 v166, v152, v166
	v_fmac_f32_e32 v168, 0x3fb8aa3b, v135
	v_med3_f32 v135, v167, v162, v164
	v_add_f32_e32 v166, v153, v166
	v_cndmask_b32_e32 v134, 0, v134, vcc
	v_cmp_eq_f32_e32 vcc, v135, v167
	v_exp_f32_e32 v135, v168
	v_add_f32_e32 v166, v146, v166
	v_add_f32_e32 v167, 0x42a40000, v163
	v_add_f32_e32 v166, v147, v166
	v_fma_f32 v168, v165, |v167|, v239
	v_add_f32_e32 v166, v148, v166
	v_fmac_f32_e32 v168, 0x3fb8aa3b, v136
	v_med3_f32 v136, v167, v162, v164
	v_add_f32_e32 v166, v149, v166
	v_cndmask_b32_e32 v135, 0, v135, vcc
	v_cmp_eq_f32_e32 vcc, v136, v167
	v_exp_f32_e32 v136, v168
	v_add_f32_e32 v166, v142, v166
	v_add_f32_e32 v167, 0x42a60000, v163
	v_add_f32_e32 v166, v143, v166
	v_fma_f32 v168, v165, |v167|, v239
	v_add_f32_e32 v166, v144, v166
	v_fmac_f32_e32 v168, 0x3fb8aa3b, v137
	v_med3_f32 v137, v167, v162, v164
	v_add_f32_e32 v166, v145, v166
	v_cndmask_b32_e32 v136, 0, v136, vcc
	v_cmp_eq_f32_e32 vcc, v137, v167
	v_exp_f32_e32 v137, v168
	v_add_f32_e32 v166, v138, v166
	v_add_f32_e32 v167, 0x42c00000, v163
	v_add_f32_e32 v166, v139, v166
	v_fma_f32 v168, v165, |v167|, v239
	v_add_f32_e32 v166, v140, v166
	v_fmac_f32_e32 v168, 0x3fb8aa3b, v130
	v_med3_f32 v130, v167, v162, v164
	v_add_f32_e32 v166, v141, v166
	v_cndmask_b32_e32 v137, 0, v137, vcc
	v_cmp_eq_f32_e32 vcc, v130, v167
	v_exp_f32_e32 v130, v168
	v_add_f32_e32 v166, v134, v166
	v_add_f32_e32 v166, v135, v166
	v_add_f32_e32 v166, v136, v166
	v_add_f32_e32 v166, v137, v166
	v_cndmask_b32_e32 v167, 0, v130, vcc
	v_add_f32_e32 v130, v167, v166
	v_add_f32_e32 v166, 0x42c20000, v163
	v_fma_f32 v168, v165, |v166|, v239
	v_fmac_f32_e32 v168, 0x3fb8aa3b, v131
	v_med3_f32 v131, v166, v162, v164
	v_cmp_eq_f32_e32 vcc, v131, v166
	v_exp_f32_e32 v131, v168
	v_cvt_pk_bf16_f32 v154, v154, v155
	v_cvt_pk_bf16_f32 v155, v156, v157
	v_cvt_pk_bf16_f32 v156, v150, v151
	v_cvt_pk_bf16_f32 v157, v152, v153
	s_xor_b64 s[6:7], s[6:7], -1
	v_cndmask_b32_e32 v166, 0, v131, vcc
	v_add_f32_e32 v131, 0x42c40000, v163
	v_fma_f32 v168, v165, |v131|, v239
	v_fmac_f32_e32 v168, 0x3fb8aa3b, v132
	v_med3_f32 v132, v131, v162, v164
	v_cmp_eq_f32_e32 vcc, v132, v131
	v_exp_f32_e32 v131, v168
	v_add_f32_e32 v130, v166, v130
	v_cndmask_b32_e32 v168, 0, v131, vcc
	v_add_f32_e32 v131, 0x42c60000, v163
	v_fma_f32 v132, v165, |v131|, v239
	v_fmac_f32_e32 v132, 0x3fb8aa3b, v133
	v_med3_f32 v133, v131, v162, v164
	v_cmp_eq_f32_e32 vcc, v133, v131
	v_exp_f32_e32 v131, v132
	v_add_f32_e32 v130, v168, v130
	v_cndmask_b32_e32 v169, 0, v131, vcc
	v_add_f32_e32 v131, 0x42e00000, v163
	v_fma_f32 v132, v165, |v131|, v239
	v_fmac_f32_e32 v132, 0x3fb8aa3b, v126
	v_med3_f32 v126, v131, v162, v164
	v_cmp_eq_f32_e32 vcc, v126, v131
	v_exp_f32_e32 v126, v132
	v_add_f32_e32 v130, v169, v130
	v_cndmask_b32_e32 v170, 0, v126, vcc
	v_add_f32_e32 v126, v170, v130
	v_add_f32_e32 v130, 0x42e20000, v163
	v_fma_f32 v131, v165, |v130|, v239
	v_fmac_f32_e32 v131, 0x3fb8aa3b, v127
	v_med3_f32 v127, v130, v162, v164
	v_cmp_eq_f32_e32 vcc, v127, v130
	v_exp_f32_e32 v127, v131
	s_nop 0
	v_cndmask_b32_e32 v171, 0, v127, vcc
	v_add_f32_e32 v127, 0x42e40000, v163
	v_fma_f32 v130, v165, |v127|, v239
	v_fmac_f32_e32 v130, 0x3fb8aa3b, v128
	v_med3_f32 v128, v127, v162, v164
	v_cmp_eq_f32_e32 vcc, v128, v127
	v_exp_f32_e32 v127, v130
	v_add_f32_e32 v126, v171, v126
	v_cvt_pk_bf16_f32 v130, v146, v147
	v_cvt_pk_bf16_f32 v131, v148, v149
	v_cndmask_b32_e32 v172, 0, v127, vcc
	v_add_f32_e32 v127, 0x42e60000, v163
	v_fma_f32 v128, v165, |v127|, v239
	v_fmac_f32_e32 v128, 0x3fb8aa3b, v129
	v_med3_f32 v129, v127, v162, v164
	v_cmp_eq_f32_e32 vcc, v129, v127
	v_exp_f32_e32 v127, v128
	v_add_f32_e32 v126, v172, v126
	v_cvt_pk_bf16_f32 v132, v142, v143
	v_cvt_pk_bf16_f32 v133, v144, v145
	v_cndmask_b32_e32 v173, 0, v127, vcc
	v_add_f32_e32 v127, 0x43000000, v163
	v_fma_f32 v128, v165, |v127|, v239
	v_fmac_f32_e32 v128, 0x3fb8aa3b, v122
	v_med3_f32 v122, v127, v162, v164
	v_cmp_eq_f32_e32 vcc, v122, v127
	v_exp_f32_e32 v122, v128
	v_add_f32_e32 v127, 0x43010000, v163
	v_fma_f32 v128, v165, |v127|, v239
	v_fmac_f32_e32 v128, 0x3fb8aa3b, v123
	v_med3_f32 v123, v127, v162, v164
	v_cndmask_b32_e32 v122, 0, v122, vcc
	v_cmp_eq_f32_e32 vcc, v123, v127
	v_exp_f32_e32 v123, v128
	v_add_f32_e32 v127, 0x43020000, v163
	v_fma_f32 v128, v165, |v127|, v239
	v_fmac_f32_e32 v128, 0x3fb8aa3b, v124
	v_med3_f32 v124, v127, v162, v164
	v_cndmask_b32_e32 v123, 0, v123, vcc
	v_cmp_eq_f32_e32 vcc, v124, v127
	v_exp_f32_e32 v124, v128
	v_add_f32_e32 v127, 0x43030000, v163
	v_fma_f32 v128, v165, |v127|, v239
	v_fmac_f32_e32 v128, 0x3fb8aa3b, v125
	v_med3_f32 v125, v127, v162, v164
	v_cndmask_b32_e32 v124, 0, v124, vcc
	v_cmp_eq_f32_e32 vcc, v125, v127
	v_exp_f32_e32 v125, v128
	v_add_f32_e32 v126, v173, v126
	v_add_f32_e32 v126, v122, v126
	v_add_f32_e32 v126, v123, v126
	v_add_f32_e32 v126, v124, v126
	v_cndmask_b32_e32 v125, 0, v125, vcc
	v_add_f32_e32 v174, v125, v126
	v_add_f32_e32 v126, 0x43100000, v163
	v_fma_f32 v127, v165, |v126|, v239
	v_fmac_f32_e32 v127, 0x3fb8aa3b, v118
	v_med3_f32 v118, v126, v162, v164
	v_cmp_eq_f32_e32 vcc, v118, v126
	v_exp_f32_e32 v118, v127
	s_nop 0
	v_cndmask_b32_e32 v175, 0, v118, vcc
	v_add_f32_e32 v118, 0x43110000, v163
	v_fma_f32 v126, v165, |v118|, v239
; #define LAS __attribute__((address_space(3)))
; __device__ __forceinline__ unsigned pk2(float lo, float hi) { return pg8::cvt_pk_bf16(lo, hi); }
; #define MFMA16(a, b, c) __builtin_amdgcn_mfma_f32_16x16x32_bf16((a), (b), (c), 0, 0, 0)
; __device__ __forceinline__ bf16x8 ds_tr2(LAS unsigned char* p, int rstride) { const s16x4 a = ds_tr(p), b = ds_tr(p + 16 * rstride); bf16x8 r; r[0] = a[0]; r[1] = a[1]; r[2] = a[2]; r[3] = a[3]; r[4] = b[0]; r[5] = b[1]; r[6] = b[2]; r[7] = b[3]; return r; }
; __device__ __forceinline__ void attention_item(LAS unsigned char* lds, const bf16* ZH, bf16* OP, float* LP, bf16* MIX, const float* qg, const float* kg, int item, int tid0) {
;     ...
;             for (int rr = 0; rr < 4; ++rr) { const float relf = rbf + (float)(16 * t + rr);
;                 const float x = __builtin_fmaf(sT[t][rr], L2E, __builtin_fmaf(-sdl, __builtin_fabsf(relf), -sml));
;                 const bool ok = __builtin_amdgcn_fmed3f(relf, LO, HI) == relf;
;                 const float p = ok ? __builtin_amdgcn_exp2f(x) : 0.f; sT[t][rr] = p; lsum += p; } }
;         bf16x8 pt[5];
; #pragma unroll
;         for (int k = 0; k < 5; ++k) { v4u o; o.x = pk2(sT[2 * k][0], sT[2 * k][1]); o.y = pk2(sT[2 * k][2], sT[2 * k][3]); o.z = pk2(sT[2 * k + 1][0], sT[2 * k + 1][1]); o.w = pk2(sT[2 * k + 1][2], sT[2 * k + 1][3]); pt[k] = __builtin_bit_cast(bf16x8, o); }
;         f32x4 o[8];
;         { LAS unsigned char* trp = lds + A_V + (4 * lg + ((l & 15) >> 2)) * RSB + (l & 3) * 8;
; #pragma unroll
;           for (int e = 0; e < 8; ++e) o[e] = (f32x4){0.f, 0.f, 0.f, 0.f};
; #pragma unroll
;           for (int k = 0; k < 5; ++k) { const int rowb = (16 * jt0 + 32 * k + off) & 255;
; #pragma unroll
;             for (int e = 0; e < 8; ++e) { const bf16x8 vf = ds_tr2(trp + rowb * RSB + (16 * e) * 2, RSB); o[e] = MFMA16(vf, pt[k], o[e]);
;                 if (e == 3) __builtin_amdgcn_sched_barrier(0); }
;             __builtin_amdgcn_sched_barrier(0); } }
	v_fmac_f32_e32 v126, 0x3fb8aa3b, v119
	v_med3_f32 v119, v118, v162, v164
	v_cmp_eq_f32_e32 vcc, v119, v118
	v_exp_f32_e32 v118, v126
	v_cvt_pk_bf16_f32 v126, v138, v139
	v_cvt_pk_bf16_f32 v127, v140, v141
	v_cvt_pk_bf16_f32 v128, v134, v135
	v_add_f32_e32 v134, v175, v174
	v_cndmask_b32_e32 v176, 0, v118, vcc
	v_add_f32_e32 v118, 0x43120000, v163
	v_fma_f32 v119, v165, |v118|, v239
	v_fmac_f32_e32 v119, 0x3fb8aa3b, v120
	v_med3_f32 v120, v118, v162, v164
	v_cmp_eq_f32_e32 vcc, v120, v118
	v_exp_f32_e32 v118, v119
	v_add_f32_e32 v134, v176, v134
	v_lshlrev_b32_e32 v135, 3, v161
	v_and_b32_e32 v135, 24, v135
	v_cndmask_b32_e32 v177, 0, v118, vcc
	v_add_f32_e32 v118, 0x43130000, v163
	v_fma_f32 v119, v165, |v118|, v239
	v_fmac_f32_e32 v119, 0x3fb8aa3b, v121
	v_med3_f32 v120, v118, v162, v164
	v_add_f32_e32 v150, v177, v134
	v_lshrrev_b32_e32 v134, 2, v2
	v_cmp_eq_f32_e32 vcc, v120, v118
	v_exp_f32_e32 v118, v119
	v_or_b32_e32 v134, v160, v134
	v_mul_u32_u24_e32 v134, 0x120, v134
	v_add3_u32 v134, s92, v134, v135
	v_mad_u32_u24 v135, v158, s74, v134
	ds_read_b64_tr_b16 v[208:209], v135 offset:4608
	ds_read_b64_tr_b16 v[206:207], v135
	ds_read_b64_tr_b16 v[210:211], v135 offset:32
	ds_read_b64_tr_b16 v[212:213], v135 offset:4640
	ds_read_b64_tr_b16 v[214:215], v135 offset:64
	ds_read_b64_tr_b16 v[216:217], v135 offset:4672
	ds_read_b64_tr_b16 v[218:219], v135 offset:96
	ds_read_b64_tr_b16 v[220:221], v135 offset:4704
	ds_read_b64_tr_b16 v[222:223], v135 offset:128
	ds_read_b64_tr_b16 v[224:225], v135 offset:4736
	ds_read_b64_tr_b16 v[242:243], v135 offset:4768
	ds_read_b64_tr_b16 v[240:241], v135 offset:160
	ds_read_b64_tr_b16 v[244:245], v135 offset:192
	ds_read_b64_tr_b16 v[248:249], v135 offset:224
	ds_read_b64_tr_b16 v[246:247], v135 offset:4800
	ds_read_b64_tr_b16 v[250:251], v135 offset:4832
	v_cndmask_b32_e32 v162, 0, v118, vcc
	v_cvt_pk_bf16_f32 v129, v136, v137
	v_cvt_pk_bf16_f32 v118, v167, v166
	v_cvt_pk_bf16_f32 v119, v168, v169
	v_cvt_pk_bf16_f32 v120, v170, v171
	v_cvt_pk_bf16_f32 v121, v172, v173
	v_cvt_pk_bf16_f32 v122, v122, v123
	v_cvt_pk_bf16_f32 v123, v124, v125
	v_cvt_pk_bf16_f32 v124, v175, v176
	v_cvt_pk_bf16_f32 v125, v177, v162
	s_waitcnt lgkmcnt(14)
	v_mfma_f32_16x16x32_bf16 v[136:139], v[206:209], v[154:157], 0
	s_waitcnt lgkmcnt(12)
	v_mfma_f32_16x16x32_bf16 v[140:143], v[210:213], v[154:157], 0
	s_waitcnt lgkmcnt(10)
	v_mfma_f32_16x16x32_bf16 v[144:147], v[214:217], v[154:157], 0
	s_waitcnt lgkmcnt(8)
	v_mfma_f32_16x16x32_bf16 v[164:167], v[218:221], v[154:157], 0
	s_waitcnt lgkmcnt(4)
	v_mfma_f32_16x16x32_bf16 v[172:175], v[240:243], v[154:157], 0
	s_waitcnt lgkmcnt(1)
	v_mfma_f32_16x16x32_bf16 v[176:179], v[244:247], v[154:157], 0
	v_mfma_f32_16x16x32_bf16 v[168:171], v[222:225], v[154:157], 0
	s_waitcnt lgkmcnt(0)
	v_mfma_f32_16x16x32_bf16 v[152:155], v[248:251], v[154:157], 0
	v_add_u32_e32 v135, 32, v159
	v_and_b32_e32 v135, 0xe0, v135
	v_mad_u32_u24 v135, v135, s74, v134
	ds_read_b64_tr_b16 v[208:209], v135 offset:4608
	ds_read_b64_tr_b16 v[206:207], v135
	ds_read_b64_tr_b16 v[210:211], v135 offset:32
	ds_read_b64_tr_b16 v[212:213], v135 offset:4640
	ds_read_b64_tr_b16 v[214:215], v135 offset:64
	ds_read_b64_tr_b16 v[216:217], v135 offset:4672
	ds_read_b64_tr_b16 v[218:219], v135 offset:96
	ds_read_b64_tr_b16 v[220:221], v135 offset:4704
	ds_read_b64_tr_b16 v[242:243], v135 offset:4736
	ds_read_b64_tr_b16 v[240:241], v135 offset:128
	ds_read_b64_tr_b16 v[244:245], v135 offset:192
	ds_read_b64_tr_b16 v[246:247], v135 offset:4800
	ds_read_b64_tr_b16 v[222:223], v135 offset:224
	ds_read_b64_tr_b16 v[224:225], v135 offset:4832
	s_waitcnt lgkmcnt(12)
	v_mfma_f32_16x16x32_bf16 v[136:139], v[206:209], v[130:133], v[136:139]
	s_waitcnt lgkmcnt(8)
	v_mfma_f32_16x16x32_bf16 v[144:147], v[214:217], v[130:133], v[144:147]
	v_mfma_f32_16x16x32_bf16 v[140:143], v[210:213], v[130:133], v[140:143]
	s_waitcnt lgkmcnt(6)
	v_mfma_f32_16x16x32_bf16 v[164:167], v[218:221], v[130:133], v[164:167]
	ds_read_b64_tr_b16 v[184:185], v135 offset:160
	ds_read_b64_tr_b16 v[186:187], v135 offset:4768
	s_waitcnt lgkmcnt(6)
	v_mfma_f32_16x16x32_bf16 v[168:171], v[240:243], v[130:133], v[168:171]
	s_waitcnt lgkmcnt(4)
	v_mfma_f32_16x16x32_bf16 v[176:179], v[244:247], v[130:133], v[176:179]
	s_waitcnt lgkmcnt(0)
	v_mfma_f32_16x16x32_bf16 v[172:175], v[184:187], v[130:133], v[172:175]
	v_mfma_f32_16x16x32_bf16 v[130:133], v[222:225], v[130:133], v[152:155]
	v_add_u32_e32 v135, 64, v159
	v_and_b32_e32 v135, 0xe0, v135
	v_mad_u32_u24 v135, v135, s74, v134
	ds_read_b64_tr_b16 v[250:251], v135 offset:4608
	ds_read_b64_tr_b16 v[248:249], v135
	ds_read_b64_tr_b16 v[206:207], v135 offset:32
	ds_read_b64_tr_b16 v[208:209], v135 offset:4640
	ds_read_b64_tr_b16 v[214:215], v135 offset:64
	ds_read_b64_tr_b16 v[216:217], v135 offset:4672
	ds_read_b64_tr_b16 v[210:211], v135 offset:96
	ds_read_b64_tr_b16 v[212:213], v135 offset:4704
	ds_read_b64_tr_b16 v[220:221], v135 offset:4736
	ds_read_b64_tr_b16 v[218:219], v135 offset:128
	ds_read_b64_tr_b16 v[240:241], v135 offset:160
	ds_read_b64_tr_b16 v[242:243], v135 offset:4768
	ds_read_b64_tr_b16 v[244:245], v135 offset:192
	ds_read_b64_tr_b16 v[246:247], v135 offset:4800
	s_waitcnt lgkmcnt(12)
	v_mfma_f32_16x16x32_bf16 v[136:139], v[248:251], v[126:129], v[136:139]
	ds_read_b64_tr_b16 v[222:223], v135 offset:224
	ds_read_b64_tr_b16 v[224:225], v135 offset:4832
	s_waitcnt lgkmcnt(10)
	v_mfma_f32_16x16x32_bf16 v[144:147], v[214:217], v[126:129], v[144:147]
	v_mfma_f32_16x16x32_bf16 v[140:143], v[206:209], v[126:129], v[140:143]
	s_waitcnt lgkmcnt(8)
	v_mfma_f32_16x16x32_bf16 v[152:155], v[210:213], v[126:129], v[164:167]
	s_nop 2
	s_waitcnt lgkmcnt(6)
; #define GAS __attribute__((address_space(1)))
; __device__ __forceinline__ unsigned pk2(float lo, float hi) { return pg8::cvt_pk_bf16(lo, hi); }
; #define MFMA16(a, b, c) __builtin_amdgcn_mfma_f32_16x16x32_bf16((a), (b), (c), 0, 0, 0)
; __device__ __forceinline__ bf16x8 ds_tr2(LAS unsigned char* p, int rstride) { const s16x4 a = ds_tr(p), b = ds_tr(p + 16 * rstride); bf16x8 r; r[0] = a[0]; r[1] = a[1]; r[2] = a[2]; r[3] = a[3]; r[4] = b[0]; r[5] = b[1]; r[6] = b[2]; r[7] = b[3]; return r; }
; __device__ __forceinline__ void attention_item(LAS unsigned char* lds, const bf16* ZH, bf16* OP, float* LP, bf16* MIX, const float* qg, const float* kg, int item, int tid0) {
;     ...
;           for (int k = 0; k < 5; ++k) { const int rowb = (16 * jt0 + 32 * k + off) & 255;
; #pragma unroll
;             for (int e = 0; e < 8; ++e) { const bf16x8 vf = ds_tr2(trp + rowb * RSB + (16 * e) * 2, RSB); o[e] = MFMA16(vf, pt[k], o[e]);
;                 if (e == 3) __builtin_amdgcn_sched_barrier(0); }
;             __builtin_amdgcn_sched_barrier(0); } }
;         lsum += __shfl_xor(lsum, 16); lsum += __shfl_xor(lsum, 32);
;         const int row = rowbase + B.r + B.d * (B.qi0 + 16 * w + lr);
;         if (B.dsh != 0) {
;             const int pb = B.dsh == 4 ? 0 : 1;
;             bf16* op = OP + ((size_t)pb * M + row) * 2048 + h * HD + 4 * lg;
; #pragma unroll
;             for (int e = 0; e < 8; ++e) { v2u ov; ov.x = pk2(o[e][0], o[e][1]); ov.y = pk2(o[e][2], o[e][3]); *(GAS v2u*)(op + 16 * e) = ov; }
;             if (lg == 0) LP[((size_t)pb * NH + h) * M + row] = lsum;
	v_mfma_f32_16x16x32_bf16 v[164:167], v[218:221], v[126:129], v[168:171]
	s_waitcnt lgkmcnt(4)
	v_mfma_f32_16x16x32_bf16 v[168:171], v[240:243], v[126:129], v[172:175]
	s_nop 2
	s_waitcnt lgkmcnt(2)
	v_mfma_f32_16x16x32_bf16 v[172:175], v[244:247], v[126:129], v[176:179]
	s_nop 2
	s_waitcnt lgkmcnt(0)
	v_mfma_f32_16x16x32_bf16 v[126:129], v[222:225], v[126:129], v[130:133]
	s_nop 2
	v_add_u32_e32 v130, 0x60, v159
	v_and_b32_e32 v130, 0xe0, v130
	v_mad_u32_u24 v135, v130, s74, v134
	ds_read_b64_tr_b16 v[250:251], v135 offset:4608
	ds_read_b64_tr_b16 v[248:249], v135
	ds_read_b64_tr_b16 v[214:215], v135 offset:32
	ds_read_b64_tr_b16 v[216:217], v135 offset:4640
	ds_read_b64_tr_b16 v[206:207], v135 offset:64
	ds_read_b64_tr_b16 v[208:209], v135 offset:4672
	ds_read_b64_tr_b16 v[210:211], v135 offset:96
	ds_read_b64_tr_b16 v[212:213], v135 offset:4704
	ds_read_b64_tr_b16 v[220:221], v135 offset:4736
	ds_read_b64_tr_b16 v[218:219], v135 offset:128
	ds_read_b64_tr_b16 v[240:241], v135 offset:160
	ds_read_b64_tr_b16 v[242:243], v135 offset:4768
	ds_read_b64_tr_b16 v[244:245], v135 offset:192
	ds_read_b64_tr_b16 v[246:247], v135 offset:4800
	s_waitcnt lgkmcnt(12)
	v_mfma_f32_16x16x32_bf16 v[130:133], v[248:251], v[118:121], v[136:139]
	ds_read_b64_tr_b16 v[222:223], v135 offset:224
	ds_read_b64_tr_b16 v[224:225], v135 offset:4832
	s_waitcnt lgkmcnt(12)
	v_mfma_f32_16x16x32_bf16 v[136:139], v[214:217], v[118:121], v[140:143]
	s_nop 2
	s_waitcnt lgkmcnt(10)
	v_mfma_f32_16x16x32_bf16 v[176:179], v[206:209], v[118:121], v[144:147]
	s_waitcnt lgkmcnt(8)
	v_mfma_f32_16x16x32_bf16 v[152:155], v[210:213], v[118:121], v[152:155]
	s_waitcnt lgkmcnt(6)
	v_mfma_f32_16x16x32_bf16 v[164:167], v[218:221], v[118:121], v[164:167]
	s_waitcnt lgkmcnt(2)
	v_mfma_f32_16x16x32_bf16 v[172:175], v[244:247], v[118:121], v[172:175]
	v_mfma_f32_16x16x32_bf16 v[168:171], v[240:243], v[118:121], v[168:171]
	s_waitcnt lgkmcnt(0)
	v_mfma_f32_16x16x32_bf16 v[180:183], v[222:225], v[118:121], v[126:129]
	v_xor_b32_e32 v118, 0x80, v158
	v_mad_u32_u24 v151, v118, s74, v134
	ds_read_b64_tr_b16 v[250:251], v151 offset:4608
	ds_read_b64_tr_b16 v[248:249], v151
	ds_read_b64_tr_b16 v[214:215], v151 offset:32
	ds_read_b64_tr_b16 v[216:217], v151 offset:4640
	ds_read_b64_tr_b16 v[206:207], v151 offset:64
	ds_read_b64_tr_b16 v[208:209], v151 offset:4672
	ds_read_b64_tr_b16 v[210:211], v151 offset:96
	ds_read_b64_tr_b16 v[212:213], v151 offset:4704
	ds_read_b64_tr_b16 v[220:221], v151 offset:4736
	ds_read_b64_tr_b16 v[218:219], v151 offset:128
	ds_read_b64_tr_b16 v[244:245], v151 offset:160
	ds_read_b64_tr_b16 v[246:247], v151 offset:4768
	ds_read_b64_tr_b16 v[240:241], v151 offset:192
	ds_read_b64_tr_b16 v[242:243], v151 offset:4800
	s_waitcnt lgkmcnt(12)
	v_mfma_f32_16x16x32_bf16 v[146:149], v[248:251], v[122:125], v[130:133]
	s_waitcnt lgkmcnt(10)
	v_mfma_f32_16x16x32_bf16 v[142:145], v[214:217], v[122:125], v[136:139]
	s_waitcnt lgkmcnt(8)
	v_mfma_f32_16x16x32_bf16 v[134:137], v[206:209], v[122:125], v[176:179]
	s_waitcnt lgkmcnt(6)
	v_mfma_f32_16x16x32_bf16 v[138:141], v[210:213], v[122:125], v[152:155]
	s_waitcnt lgkmcnt(4)
	v_mfma_f32_16x16x32_bf16 v[130:133], v[218:221], v[122:125], v[164:167]
	ds_read_b64_tr_b16 v[152:153], v151 offset:224
	ds_read_b64_tr_b16 v[154:155], v151 offset:4832
	s_waitcnt lgkmcnt(4)
	v_mfma_f32_16x16x32_bf16 v[126:129], v[244:247], v[122:125], v[168:171]
	s_waitcnt lgkmcnt(2)
	v_mfma_f32_16x16x32_bf16 v[118:121], v[240:243], v[122:125], v[172:175]
	s_waitcnt lgkmcnt(0)
	v_mfma_f32_16x16x32_bf16 v[122:125], v[152:155], v[122:125], v[180:183]
	v_add_f32_e32 v150, v162, v150
	ds_bpermute_b32 v151, v205, v150
	v_or_b32_e32 v2, s34, v2
	v_add_lshl_u32 v2, v2, v5, s42
	s_add_i32 s28, s28, s20
	v_add_u32_e32 v172, s28, v2
	s_waitcnt lgkmcnt(0)
	v_add_f32_e32 v150, v150, v151
	ds_bpermute_b32 v151, v226, v150
	s_mov_b64 s[34:35], -1
	s_andn2_b64 vcc, exec, s[6:7]
	v_ashrrev_i32_e32 v173, 31, v172
	v_lshlrev_b32_e32 v2, 1, v160
	s_waitcnt lgkmcnt(0)
	v_add_f32_e32 v178, v150, v151
	s_cbranch_vccnz .LBB0_442
	s_and_b64 s[6:7], exec, s[40:41]
	s_cselect_b32 s28, 0, 0x4000
	v_lshl_add_u64 v[150:151], s[28:29], 0, v[172:173]
	v_lshlrev_b64 v[150:151], 12, v[150:151]
	v_lshl_add_u64 v[150:151], s[72:73], 0, v[150:151]
	v_and_b32_e32 v152, 16, v0
	v_lshrrev_b32_e32 v153, 1, v152
	v_add3_u32 v2, v2, v152, v153
	v_lshl_add_u64 v[150:151], v[150:151], 0, v[2:3]
	v_cvt_pk_bf16_f32 v146, v146, v147
	v_cvt_pk_bf16_f32 v147, v148, v149
	v_cvt_pk_bf16_f32 v148, v142, v143
	v_cvt_pk_bf16_f32 v149, v144, v145
	s_nop 1
	v_permlane16_swap_b32_e32 v146, v148
	v_permlane16_swap_b32_e32 v147, v149
	global_store_dwordx4 v[150:151], v[146:149], off
	v_cvt_pk_bf16_f32 v134, v134, v135
	v_cvt_pk_bf16_f32 v135, v136, v137
	v_cvt_pk_bf16_f32 v136, v138, v139
	v_cvt_pk_bf16_f32 v137, v140, v141
	s_nop 1
	v_permlane16_swap_b32_e32 v134, v136
	v_permlane16_swap_b32_e32 v135, v137
	global_store_dwordx4 v[150:151], v[134:137], off offset:64
	v_cvt_pk_bf16_f32 v130, v130, v131
	v_cvt_pk_bf16_f32 v131, v132, v133
	v_cvt_pk_bf16_f32 v132, v126, v127
	v_cvt_pk_bf16_f32 v133, v128, v129
	s_nop 1
	v_permlane16_swap_b32_e32 v130, v132
	v_permlane16_swap_b32_e32 v131, v133
	global_store_dwordx4 v[150:151], v[130:133], off offset:128
	v_cvt_pk_bf16_f32 v118, v118, v119
	v_cvt_pk_bf16_f32 v119, v120, v121
	v_cvt_pk_bf16_f32 v120, v122, v123
	v_cvt_pk_bf16_f32 v121, v124, v125
	s_nop 1
	v_permlane16_swap_b32_e32 v118, v120
	v_permlane16_swap_b32_e32 v119, v121
	global_store_dwordx4 v[150:151], v[118:121], off offset:192
	v_cmp_eq_u32_e32 vcc, 0, v4
	s_and_saveexec_b64 s[6:7], vcc
	s_cbranch_execz .LBB0_441
	s_and_b64 s[34:35], exec, s[40:41]
	s_cselect_b32 s28, 0, 16
	s_or_b32 s28, s28, s46
	s_lshl_b32 s28, s28, 16
	s_add_u32 s34, s21, s28
	s_addc_u32 s35, s65, 0
	v_lshl_add_u64 v[4:5], v[172:173], 2, s[34:35]
	global_store_dword v[4:5], v178, off
